# P2/P6 K-loops rotated: next tile's first fragment reads issued right after the barrier, before the last 8 MFMAs
# speedup vs baseline: 1.0449x; 1.0000x over previous
; #define MFMA(a, b, c) __builtin_amdgcn_mfma_f32_32x32x16_bf16((a), (b), (c), 0, 0, 0)
; #define G_BARRIER() { asm volatile("s_waitcnt vmcnt(0) lgkmcnt(0)" ::: "memory"); __builtin_amdgcn_s_barrier(); asm volatile("" ::: "memory"); }
;     ...
;         f32x16 acc[2][TB];
; #pragma unroll
;         for (int a = 0; a < 2; ++a)
; #pragma unroll
;             for (int b = 0; b < TB; ++b)
; #pragma unroll
;                 for (int i = 0; i < 16; ++i) acc[a][b][i] = 0.f;
;         G_BARRIER();
;         for (int kt = 0; kt < nk; ++kt) {
;             if (kt + 1 < nk) { G_DMA(kt + 1, (kt + 1) & 1); }
;             const unsigned char* sa = lds + (kt & 1) * 65536 + (wt * 32 * TB + r) * 128;
;             const unsigned char* sw = lds + (kt & 1) * 65536 + 32768 + (wf * 64 + r) * 128;
; #pragma unroll
;             for (int ks = 0; ks < 4; ++ks) {
;                 bf16x8 wfr[2], afr[TB];
; #pragma unroll
;                 for (int fb = 0; fb < 2; ++fb) wfr[fb] = *(const bf16x8*)(sw + fb * 4096 + koff[ks]);
; #pragma unroll
;                 for (int tb = 0; tb < TB; ++tb) afr[tb] = *(const bf16x8*)(sa + tb * 4096 + koff[ks]);
; #pragma unroll
;                 for (int fb = 0; fb < 2; ++fb)
; #pragma unroll
;                     for (int tb = 0; tb < TB; ++tb) acc[fb][tb] = MFMA(wfr[fb], afr[tb], acc[fb][tb]);
;             }
;             G_BARRIER();
;         }
.LBB0_201:
	s_waitcnt vmcnt(0) lgkmcnt(0)
	s_barrier
	v_mov_b32_e32 v0, 0
	s_mov_b32 s7, 0
	s_mov_b64 s[4:5], 0
	v_mov_b32_e32 v1, v0
	v_mov_b32_e32 v2, v0
	v_mov_b32_e32 v3, v0
	v_mov_b32_e32 v4, v0
	v_mov_b32_e32 v5, v0
	v_mov_b32_e32 v6, v0
	v_mov_b32_e32 v7, v0
	v_mov_b32_e32 v8, v0
	v_mov_b32_e32 v9, v0
	v_mov_b32_e32 v10, v0
	v_mov_b32_e32 v11, v0
	v_mov_b32_e32 v12, v0
	v_mov_b32_e32 v13, v0
	v_mov_b32_e32 v14, v0
	v_mov_b32_e32 v15, v0
	v_mov_b32_e32 v16, v0
	v_mov_b32_e32 v17, v0
	v_mov_b32_e32 v18, v0
	v_mov_b32_e32 v19, v0
	v_mov_b32_e32 v20, v0
	v_mov_b32_e32 v21, v0
	v_mov_b32_e32 v22, v0
	v_mov_b32_e32 v23, v0
	v_mov_b32_e32 v24, v0
	v_mov_b32_e32 v25, v0
	v_mov_b32_e32 v26, v0
	v_mov_b32_e32 v27, v0
	v_mov_b32_e32 v28, v0
	v_mov_b32_e32 v29, v0
	v_mov_b32_e32 v30, v0
	v_mov_b32_e32 v31, v0
	v_mov_b32_e32 v32, v0
	v_mov_b32_e32 v33, v0
	v_mov_b32_e32 v34, v0
	v_mov_b32_e32 v35, v0
	v_mov_b32_e32 v36, v0
	v_mov_b32_e32 v37, v0
	v_mov_b32_e32 v38, v0
	v_mov_b32_e32 v39, v0
	v_mov_b32_e32 v40, v0
	v_mov_b32_e32 v41, v0
	v_mov_b32_e32 v42, v0
	v_mov_b32_e32 v43, v0
	v_mov_b32_e32 v44, v0
	v_mov_b32_e32 v45, v0
	v_mov_b32_e32 v46, v0
	v_mov_b32_e32 v47, v0
	v_mov_b32_e32 v48, v0
	v_mov_b32_e32 v49, v0
	v_mov_b32_e32 v50, v0
	v_mov_b32_e32 v51, v0
	v_mov_b32_e32 v52, v0
	v_mov_b32_e32 v53, v0
	v_mov_b32_e32 v54, v0
	v_mov_b32_e32 v55, v0
	v_mov_b32_e32 v56, v0
	v_mov_b32_e32 v57, v0
	v_mov_b32_e32 v58, v0
	v_mov_b32_e32 v59, v0
	v_mov_b32_e32 v60, v0
	v_mov_b32_e32 v61, v0
	v_mov_b32_e32 v62, v0
	v_mov_b32_e32 v63, v0
	v_mov_b32_e32 v64, v0
	v_mov_b32_e32 v65, v0
	v_mov_b32_e32 v66, v0
	v_mov_b32_e32 v67, v0
	v_mov_b32_e32 v68, v0
	v_mov_b32_e32 v69, v0
	v_mov_b32_e32 v70, v0
	v_mov_b32_e32 v71, v0
	v_mov_b32_e32 v72, v0
	v_mov_b32_e32 v73, v0
	v_mov_b32_e32 v74, v0
	v_mov_b32_e32 v75, v0
	v_mov_b32_e32 v76, v0
	v_mov_b32_e32 v77, v0
	v_mov_b32_e32 v78, v0
	v_mov_b32_e32 v79, v0
	v_mov_b32_e32 v80, v0
	v_mov_b32_e32 v81, v0
	v_mov_b32_e32 v82, v0
	v_mov_b32_e32 v83, v0
	v_mov_b32_e32 v84, v0
	v_mov_b32_e32 v85, v0
	v_mov_b32_e32 v86, v0
	v_mov_b32_e32 v87, v0
	v_mov_b32_e32 v88, v0
	v_mov_b32_e32 v89, v0
	v_mov_b32_e32 v90, v0
	v_mov_b32_e32 v91, v0
	v_mov_b32_e32 v92, v0
	v_mov_b32_e32 v93, v0
	v_mov_b32_e32 v94, v0
	v_mov_b32_e32 v95, v0
	v_mov_b32_e32 v96, v0
	v_mov_b32_e32 v97, v0
	v_mov_b32_e32 v98, v0
	v_mov_b32_e32 v99, v0
	v_mov_b32_e32 v100, v0
	v_mov_b32_e32 v101, v0
	v_mov_b32_e32 v102, v0
	v_mov_b32_e32 v103, v0
	v_mov_b32_e32 v104, v0
	v_mov_b32_e32 v105, v0
	v_mov_b32_e32 v106, v0
	v_mov_b32_e32 v107, v0
	v_mov_b32_e32 v108, v0
	v_mov_b32_e32 v109, v0
	v_mov_b32_e32 v110, v0
	v_mov_b32_e32 v111, v0
	v_mov_b32_e32 v112, v0
	v_mov_b32_e32 v113, v0
	v_mov_b32_e32 v114, v0
	v_mov_b32_e32 v115, v0
	v_mov_b32_e32 v116, v0
	v_mov_b32_e32 v117, v0
	v_mov_b32_e32 v118, v0
	v_mov_b32_e32 v119, v0
	v_mov_b32_e32 v120, v0
	v_mov_b32_e32 v121, v0
	v_mov_b32_e32 v122, v0
	v_mov_b32_e32 v123, v0
	v_mov_b32_e32 v124, v0
	v_mov_b32_e32 v125, v0
	v_mov_b32_e32 v126, v0
	v_mov_b32_e32 v127, v0
	v_readfirstlane_b32 s74, v170
	v_readfirstlane_b32 s75, v171
	v_readfirstlane_b32 s76, v172
	v_readfirstlane_b32 s77, v173
	v_readfirstlane_b32 s32, v168
	s_nop 3
	s_sub_u32 s74, s74, s32
	s_subb_u32 s75, s75, 0
	s_add_u32 s74, s74, s4
	s_addc_u32 s75, s75, s5
	s_sub_u32 s76, s76, s32
	s_subb_u32 s77, s77, 0
	s_add_u32 s76, s76, s4
	s_addc_u32 s77, s77, s5
	v_add_u32_e32 v240, 0x80, v168
	v_add_u32_e32 v241, 0x20080, v168
	v_add_u32_e32 v242, 0x40080, v168
	v_add_u32_e32 v243, 0x60080, v168
	s_and_b32 s32, s7, 0x10000
	s_add_i32 s32, s32, 16
	v_add3_u32 v132, s32, v183, v154
	v_add3_u32 v155, s32, v184, v154
	v_add_u32_e32 v169, v155, v159
	v_add_u32_e32 v193, v132, v159
	ds_read_b128 v[128:131], v169 offset:32768
	ds_read_b128 v[174:177], v193
	ds_read_b128 v[194:197], v169 offset:36864
	ds_read_b128 v[198:201], v193 offset:4096
	ds_read_b128 v[204:207], v193 offset:8192
	ds_read_b128 v[208:211], v193 offset:12288
.LBB0_202:
	s_add_i32 s8, s7, 0x10000
	s_and_b32 s9, s8, 0x10000
	s_add_i32 s9, s23, s9
	s_mov_b32 m0, s9
	s_nop 0
	global_load_lds_dwordx4 v240, s[74:75]
	s_add_i32 m0, s9, 0x8000
	s_nop 0
	global_load_lds_dwordx4 v240, s[76:77]
	s_add_i32 m0, s9, 0x2000
	s_nop 0
	global_load_lds_dwordx4 v241, s[74:75]
	s_add_i32 m0, s9, 0xa000
	s_nop 0
	global_load_lds_dwordx4 v241, s[76:77]
	s_add_i32 m0, s9, 0x4000
	s_nop 0
	global_load_lds_dwordx4 v242, s[74:75]
	s_add_i32 m0, s9, 0xc000
	s_nop 0
	global_load_lds_dwordx4 v242, s[76:77]
	s_add_i32 m0, s9, 0x6000
	s_nop 0
	global_load_lds_dwordx4 v243, s[74:75]
	s_add_i32 m0, s9, 0xe000
	s_nop 0
	global_load_lds_dwordx4 v243, s[76:77]
	s_add_u32 s74, s74, 0x80
	s_addc_u32 s75, s75, 0
	s_add_u32 s76, s76, 0x80
	s_addc_u32 s77, s77, 0
	v_add_u32_e32 v169, v155, v161
	v_add_u32_e32 v178, v132, v161
	ds_read_b128 v[212:215], v169 offset:32768
	ds_read_b128 v[216:219], v178
	ds_read_b128 v[220:223], v169 offset:36864
	ds_read_b128 v[224:227], v178 offset:4096
	ds_read_b128 v[228:231], v178 offset:8192
	ds_read_b128 v[232:235], v178 offset:12288
	s_waitcnt lgkmcnt(6)
	v_mfma_f32_32x32x16_bf16 v[112:127], v[128:131], v[174:177], v[112:127]
	s_add_u32 s4, s4, 0x80
	s_addc_u32 s5, s5, 0
	s_and_b32 s32, s8, 0x10000
	s_add_i32 s32, s32, 16
	s_cmpk_eq_i32 s4, 0x780
	s_mov_b32 s7, s8
	v_mfma_f32_32x32x16_bf16 v[96:111], v[128:131], v[198:201], v[96:111]
	v_mfma_f32_32x32x16_bf16 v[80:95], v[128:131], v[204:207], v[80:95]
	v_mfma_f32_32x32x16_bf16 v[64:79], v[128:131], v[208:211], v[64:79]
	v_mfma_f32_32x32x16_bf16 v[48:63], v[194:197], v[174:177], v[48:63]
	v_mfma_f32_32x32x16_bf16 v[32:47], v[194:197], v[198:201], v[32:47]
	v_mfma_f32_32x32x16_bf16 v[16:31], v[194:197], v[204:207], v[16:31]
	v_mfma_f32_32x32x16_bf16 v[0:15], v[194:197], v[208:211], v[0:15]
	v_add_u32_e32 v169, v155, v180
	v_add_u32_e32 v178, v132, v180
	ds_read_b128 v[128:131], v169 offset:32768
	ds_read_b128 v[174:177], v178
	ds_read_b128 v[194:197], v169 offset:36864
	ds_read_b128 v[198:201], v178 offset:4096
	ds_read_b128 v[204:207], v178 offset:8192
	ds_read_b128 v[208:211], v178 offset:12288
	s_waitcnt lgkmcnt(6)
; #define MFMA(a, b, c) __builtin_amdgcn_mfma_f32_32x32x16_bf16((a), (b), (c), 0, 0, 0)
; #define G_BARRIER() { asm volatile("s_waitcnt vmcnt(0) lgkmcnt(0)" ::: "memory"); __builtin_amdgcn_s_barrier(); asm volatile("" ::: "memory"); }
;     ...
;         for (int kt = 0; kt < nk; ++kt) {
;             if (kt + 1 < nk) { G_DMA(kt + 1, (kt + 1) & 1); }
;             const unsigned char* sa = lds + (kt & 1) * 65536 + (wt * 32 * TB + r) * 128;
;             const unsigned char* sw = lds + (kt & 1) * 65536 + 32768 + (wf * 64 + r) * 128;
; #pragma unroll
;             for (int ks = 0; ks < 4; ++ks) {
;                 bf16x8 wfr[2], afr[TB];
; #pragma unroll
;                 for (int fb = 0; fb < 2; ++fb) wfr[fb] = *(const bf16x8*)(sw + fb * 4096 + koff[ks]);
; #pragma unroll
;                 for (int tb = 0; tb < TB; ++tb) afr[tb] = *(const bf16x8*)(sa + tb * 4096 + koff[ks]);
; #pragma unroll
;                 for (int fb = 0; fb < 2; ++fb)
; #pragma unroll
;                     for (int tb = 0; tb < TB; ++tb) acc[fb][tb] = MFMA(wfr[fb], afr[tb], acc[fb][tb]);
;             }
;             G_BARRIER();
;         }
	v_mfma_f32_32x32x16_bf16 v[112:127], v[212:215], v[216:219], v[112:127]
	v_mfma_f32_32x32x16_bf16 v[96:111], v[212:215], v[224:227], v[96:111]
	v_mfma_f32_32x32x16_bf16 v[80:95], v[212:215], v[228:231], v[80:95]
	v_mfma_f32_32x32x16_bf16 v[64:79], v[212:215], v[232:235], v[64:79]
	v_mfma_f32_32x32x16_bf16 v[48:63], v[220:223], v[216:219], v[48:63]
	v_mfma_f32_32x32x16_bf16 v[32:47], v[220:223], v[224:227], v[32:47]
	v_mfma_f32_32x32x16_bf16 v[16:31], v[220:223], v[228:231], v[16:31]
	v_mfma_f32_32x32x16_bf16 v[0:15], v[220:223], v[232:235], v[0:15]
	v_add_u32_e32 v155, v155, v181
	v_add_u32_e32 v132, v132, v181
	ds_read_b128 v[212:215], v155 offset:32768
	ds_read_b128 v[216:219], v132
	ds_read_b128 v[220:223], v155 offset:36864
	ds_read_b128 v[224:227], v132 offset:4096
	ds_read_b128 v[228:231], v132 offset:8192
	ds_read_b128 v[232:235], v132 offset:12288
	s_waitcnt lgkmcnt(6)
	v_mfma_f32_32x32x16_bf16 v[112:127], v[128:131], v[174:177], v[112:127]
	v_mfma_f32_32x32x16_bf16 v[96:111], v[128:131], v[198:201], v[96:111]
	v_mfma_f32_32x32x16_bf16 v[80:95], v[128:131], v[204:207], v[80:95]
	v_mfma_f32_32x32x16_bf16 v[64:79], v[128:131], v[208:211], v[64:79]
	v_mfma_f32_32x32x16_bf16 v[48:63], v[194:197], v[174:177], v[48:63]
	v_mfma_f32_32x32x16_bf16 v[32:47], v[194:197], v[198:201], v[32:47]
	v_mfma_f32_32x32x16_bf16 v[16:31], v[194:197], v[204:207], v[16:31]
	v_mfma_f32_32x32x16_bf16 v[0:15], v[194:197], v[208:211], v[0:15]
	s_waitcnt vmcnt(0) lgkmcnt(0)
	s_barrier
	v_add3_u32 v132, s32, v183, v154
	v_add3_u32 v155, s32, v184, v154
	v_add_u32_e32 v169, v155, v159
	v_add_u32_e32 v193, v132, v159
	ds_read_b128 v[128:131], v169 offset:32768
	ds_read_b128 v[174:177], v193
	ds_read_b128 v[194:197], v169 offset:36864
	ds_read_b128 v[198:201], v193 offset:4096
	ds_read_b128 v[204:207], v193 offset:8192
	ds_read_b128 v[208:211], v193 offset:12288
	v_mfma_f32_32x32x16_bf16 v[112:127], v[212:215], v[216:219], v[112:127]
	v_mfma_f32_32x32x16_bf16 v[96:111], v[212:215], v[224:227], v[96:111]
	v_mfma_f32_32x32x16_bf16 v[80:95], v[212:215], v[228:231], v[80:95]
	v_mfma_f32_32x32x16_bf16 v[64:79], v[212:215], v[232:235], v[64:79]
	v_mfma_f32_32x32x16_bf16 v[48:63], v[220:223], v[216:219], v[48:63]
	v_mfma_f32_32x32x16_bf16 v[32:47], v[220:223], v[224:227], v[32:47]
	v_mfma_f32_32x32x16_bf16 v[16:31], v[220:223], v[228:231], v[16:31]
	v_mfma_f32_32x32x16_bf16 v[0:15], v[220:223], v[232:235], v[0:15]
	s_cbranch_scc0 .LBB0_202
; #define GAS __attribute__((address_space(1)))
; #define MFMA(a, b, c) __builtin_amdgcn_mfma_f32_32x32x16_bf16((a), (b), (c), 0, 0, 0)
; #define G_BARRIER() { asm volatile("s_waitcnt vmcnt(0) lgkmcnt(0)" ::: "memory"); __builtin_amdgcn_s_barrier(); asm volatile("" ::: "memory"); }
;     ...
;         for (int kt = 0; kt < nk; ++kt) {
;             if (kt + 1 < nk) { G_DMA(kt + 1, (kt + 1) & 1); }
;             const unsigned char* sa = lds + (kt & 1) * 65536 + (wt * 32 * TB + r) * 128;
;             const unsigned char* sw = lds + (kt & 1) * 65536 + 32768 + (wf * 64 + r) * 128;
; #pragma unroll
;             for (int ks = 0; ks < 4; ++ks) {
;                 bf16x8 wfr[2], afr[TB];
; #pragma unroll
;                 for (int fb = 0; fb < 2; ++fb) wfr[fb] = *(const bf16x8*)(sw + fb * 4096 + koff[ks]);
; #pragma unroll
;                 for (int tb = 0; tb < TB; ++tb) afr[tb] = *(const bf16x8*)(sa + tb * 4096 + koff[ks]);
; #pragma unroll
;                 for (int fb = 0; fb < 2; ++fb)
; #pragma unroll
;                     for (int tb = 0; tb < TB; ++tb) acc[fb][tb] = MFMA(wfr[fb], afr[tb], acc[fb][tb]);
;             }
;             G_BARRIER();
;         }
;         const int un = u + nslots;
;         if (un < nloc) {
;             Ag = (const GAS bf16_t*)(A + (size_t)(xcd + nx * (un / Ntiles)) * RM * K) + dsrc; Wg = (const GAS bf16_t*)(Wt + (size_t)(un % Ntiles) * 256 * K) + dsrc;
;             G_DMA(0, 0);
;         }
	v_add_u32_e32 v132, v189, v159
	ds_read_b128 v[128:131], v132
	v_add_u32_e32 v155, v188, v159
	ds_read_b128 v[174:177], v155
	ds_read_b128 v[194:197], v155 offset:4096
	ds_read_b128 v[198:201], v155 offset:8192
	ds_read_b128 v[204:207], v155 offset:12288
	v_add_u32_e32 v155, v188, v161
	s_add_i32 s24, s6, s0
	s_cmp_ge_i32 s24, s1
	s_waitcnt lgkmcnt(0)
	v_mfma_f32_32x32x16_bf16 v[112:127], v[128:131], v[174:177], v[112:127]
	s_cselect_b64 s[96:97], -1, 0
	s_cmp_lt_i32 s24, s1
	v_mfma_f32_32x32x16_bf16 v[96:111], v[128:131], v[194:197], v[96:111]
	v_mfma_f32_32x32x16_bf16 v[80:95], v[128:131], v[198:201], v[80:95]
	v_mfma_f32_32x32x16_bf16 v[64:79], v[128:131], v[204:207], v[64:79]
	ds_read_b128 v[128:131], v132 offset:4096
	v_add_u32_e32 v132, v189, v161
	s_waitcnt lgkmcnt(0)
	v_mfma_f32_32x32x16_bf16 v[48:63], v[128:131], v[174:177], v[48:63]
	ds_read_b128 v[174:177], v155
	v_mfma_f32_32x32x16_bf16 v[32:47], v[128:131], v[194:197], v[32:47]
	ds_read_b128 v[194:197], v155 offset:4096
	v_mfma_f32_32x32x16_bf16 v[16:31], v[128:131], v[198:201], v[16:31]
	ds_read_b128 v[198:201], v155 offset:8192
	v_mfma_f32_32x32x16_bf16 v[0:15], v[128:131], v[204:207], v[0:15]
	ds_read_b128 v[128:131], v132
	ds_read_b128 v[204:207], v155 offset:12288
	v_add_u32_e32 v155, v188, v180
	s_waitcnt lgkmcnt(0)
	v_mfma_f32_32x32x16_bf16 v[112:127], v[128:131], v[174:177], v[112:127]
	v_mfma_f32_32x32x16_bf16 v[96:111], v[128:131], v[194:197], v[96:111]
	v_mfma_f32_32x32x16_bf16 v[80:95], v[128:131], v[198:201], v[80:95]
	v_mfma_f32_32x32x16_bf16 v[64:79], v[128:131], v[204:207], v[64:79]
	ds_read_b128 v[128:131], v132 offset:4096
	v_add_u32_e32 v132, v189, v180
	s_waitcnt lgkmcnt(0)
	v_mfma_f32_32x32x16_bf16 v[48:63], v[128:131], v[174:177], v[48:63]
	ds_read_b128 v[174:177], v155
	v_mfma_f32_32x32x16_bf16 v[32:47], v[128:131], v[194:197], v[32:47]
	ds_read_b128 v[194:197], v155 offset:4096
	v_mfma_f32_32x32x16_bf16 v[16:31], v[128:131], v[198:201], v[16:31]
	ds_read_b128 v[198:201], v155 offset:8192
	v_mfma_f32_32x32x16_bf16 v[0:15], v[128:131], v[204:207], v[0:15]
	ds_read_b128 v[128:131], v132
	ds_read_b128 v[204:207], v155 offset:12288
	v_add_u32_e32 v155, v188, v181
	s_waitcnt lgkmcnt(0)
	v_mfma_f32_32x32x16_bf16 v[112:127], v[128:131], v[174:177], v[112:127]
	v_mfma_f32_32x32x16_bf16 v[96:111], v[128:131], v[194:197], v[96:111]
	v_mfma_f32_32x32x16_bf16 v[80:95], v[128:131], v[198:201], v[80:95]
	v_mfma_f32_32x32x16_bf16 v[64:79], v[128:131], v[204:207], v[64:79]
	ds_read_b128 v[128:131], v132 offset:4096
	v_add_u32_e32 v132, v189, v181
	s_waitcnt lgkmcnt(0)
	v_mfma_f32_32x32x16_bf16 v[48:63], v[128:131], v[174:177], v[48:63]
	ds_read_b128 v[174:177], v155
	v_mfma_f32_32x32x16_bf16 v[32:47], v[128:131], v[194:197], v[32:47]
	ds_read_b128 v[194:197], v155 offset:4096
	v_mfma_f32_32x32x16_bf16 v[16:31], v[128:131], v[198:201], v[16:31]
	ds_read_b128 v[198:201], v155 offset:8192
	v_mfma_f32_32x32x16_bf16 v[0:15], v[128:131], v[204:207], v[0:15]
	ds_read_b128 v[128:131], v132
	ds_read_b128 v[204:207], v155 offset:12288
	s_waitcnt lgkmcnt(0)
	v_mfma_f32_32x32x16_bf16 v[112:127], v[128:131], v[174:177], v[112:127]
	v_mfma_f32_32x32x16_bf16 v[96:111], v[128:131], v[194:197], v[96:111]
	v_mfma_f32_32x32x16_bf16 v[80:95], v[128:131], v[198:201], v[80:95]
	v_mfma_f32_32x32x16_bf16 v[64:79], v[128:131], v[204:207], v[64:79]
	ds_read_b128 v[128:131], v132 offset:4096
	s_waitcnt vmcnt(0) lgkmcnt(0)
	s_barrier
	s_waitcnt lgkmcnt(0)
	v_mfma_f32_32x32x16_bf16 v[48:63], v[128:131], v[174:177], v[48:63]
	v_mfma_f32_32x32x16_bf16 v[32:47], v[128:131], v[194:197], v[32:47]
	v_mfma_f32_32x32x16_bf16 v[16:31], v[128:131], v[198:201], v[16:31]
	v_mfma_f32_32x32x16_bf16 v[0:15], v[128:131], v[204:207], v[0:15]
	s_cbranch_scc0 .LBB0_205
	s_mul_hi_i32 s4, s24, 0x66666667
	s_lshr_b32 s5, s4, 31
	s_ashr_i32 s4, s4, 2
	s_add_i32 s7, s4, s5
	s_lshl_b32 s4, s7, s68
	s_add_i32 s4, s4, s69
	s_ashr_i32 s5, s4, 31
	s_lshl_b64 s[4:5], s[4:5], 19
	s_add_u32 s4, s60, s4
	s_mul_i32 s7, s7, 10
	s_addc_u32 s5, s61, s5
	s_sub_i32 s8, s24, s7
	s_ashr_i32 s9, s8, 31
	s_lshl_b64 s[8:9], s[8:9], 19
	s_mov_b32 m0, s23
	v_mov_b32_e32 v169, v133
	s_add_u32 s8, s62, s8
	v_lshl_add_u64 v[170:171], s[4:5], 0, v[168:169]
	s_addc_u32 s9, s63, s9
	global_load_lds_dwordx4 v168, s[4:5]
	s_add_i32 m0, s23, 0x8000
	v_lshl_add_u64 v[172:173], s[8:9], 0, v[168:169]
	global_load_lds_dwordx4 v168, s[8:9]
	v_lshl_add_u64 v[128:129], v[170:171], 0, s[66:67]
	s_add_i32 m0, s23, 0x2000
	s_nop 0
	global_load_lds_dwordx4 v[128:129], off
	v_lshl_add_u64 v[128:129], v[172:173], 0, s[66:67]
	s_add_i32 m0, s23, 0xa000
	s_nop 0
	global_load_lds_dwordx4 v[128:129], off
	v_lshl_add_u64 v[128:129], v[170:171], 0, s[70:71]
	s_add_i32 m0, s23, 0x4000
	s_nop 0
	global_load_lds_dwordx4 v[128:129], off
	v_lshl_add_u64 v[128:129], v[172:173], 0, s[70:71]
	s_add_i32 m0, s23, 0xc000
	s_nop 0
	global_load_lds_dwordx4 v[128:129], off
	v_lshl_add_u64 v[128:129], v[170:171], 0, s[72:73]
	s_add_i32 m0, s23, 0x6000
	s_nop 0
	global_load_lds_dwordx4 v[128:129], off
	v_lshl_add_u64 v[128:129], v[172:173], 0, s[72:73]
	s_add_i32 m0, s23, 0xe000
	s_nop 0
	global_load_lds_dwordx4 v[128:129], off

; #define MFMA(a, b, c) __builtin_amdgcn_mfma_f32_32x32x16_bf16((a), (b), (c), 0, 0, 0)
; #define G_BARRIER() { asm volatile("s_waitcnt vmcnt(0) lgkmcnt(0)" ::: "memory"); __builtin_amdgcn_s_barrier(); asm volatile("" ::: "memory"); }
;     ...
;         f32x16 acc[2][TB];
; #pragma unroll
;         for (int a = 0; a < 2; ++a)
; #pragma unroll
;             for (int b = 0; b < TB; ++b)
; #pragma unroll
;                 for (int i = 0; i < 16; ++i) acc[a][b][i] = 0.f;
;         G_BARRIER();
;         for (int kt = 0; kt < nk; ++kt) {
;             if (kt + 1 < nk) { G_DMA(kt + 1, (kt + 1) & 1); }
;             const unsigned char* sa = lds + (kt & 1) * 65536 + (wt * 32 * TB + r) * 128;
;             const unsigned char* sw = lds + (kt & 1) * 65536 + 32768 + (wf * 64 + r) * 128;
; #pragma unroll
;             for (int ks = 0; ks < 4; ++ks) {
;                 bf16x8 wfr[2], afr[TB];
; #pragma unroll
;                 for (int fb = 0; fb < 2; ++fb) wfr[fb] = *(const bf16x8*)(sw + fb * 4096 + koff[ks]);
; #pragma unroll
;                 for (int tb = 0; tb < TB; ++tb) afr[tb] = *(const bf16x8*)(sa + tb * 4096 + koff[ks]);
; #pragma unroll
;                 for (int fb = 0; fb < 2; ++fb)
; #pragma unroll
;                     for (int tb = 0; tb < TB; ++tb) acc[fb][tb] = MFMA(wfr[fb], afr[tb], acc[fb][tb]);
;             }
;             G_BARRIER();
;         }
.LBB0_742:
	s_waitcnt vmcnt(0) lgkmcnt(0)
	s_barrier
	v_mov_b32_e32 v0, 0
	s_mov_b32 s1, s0
	s_mov_b32 s0, 0
	s_mov_b64 s[6:7], 0
	v_mov_b32_e32 v1, v0
	v_mov_b32_e32 v2, v0
	v_mov_b32_e32 v3, v0
	v_mov_b32_e32 v4, v0
	v_mov_b32_e32 v5, v0
	v_mov_b32_e32 v6, v0
	v_mov_b32_e32 v7, v0
	v_mov_b32_e32 v8, v0
	v_mov_b32_e32 v9, v0
	v_mov_b32_e32 v10, v0
	v_mov_b32_e32 v11, v0
	v_mov_b32_e32 v12, v0
	v_mov_b32_e32 v13, v0
	v_mov_b32_e32 v14, v0
	v_mov_b32_e32 v15, v0
	v_mov_b32_e32 v16, v0
	v_mov_b32_e32 v17, v0
	v_mov_b32_e32 v18, v0
	v_mov_b32_e32 v19, v0
	v_mov_b32_e32 v20, v0
	v_mov_b32_e32 v21, v0
	v_mov_b32_e32 v22, v0
	v_mov_b32_e32 v23, v0
	v_mov_b32_e32 v24, v0
	v_mov_b32_e32 v25, v0
	v_mov_b32_e32 v26, v0
	v_mov_b32_e32 v27, v0
	v_mov_b32_e32 v28, v0
	v_mov_b32_e32 v29, v0
	v_mov_b32_e32 v30, v0
	v_mov_b32_e32 v31, v0
	v_mov_b32_e32 v32, v0
	v_mov_b32_e32 v33, v0
	v_mov_b32_e32 v34, v0
	v_mov_b32_e32 v35, v0
	v_mov_b32_e32 v36, v0
	v_mov_b32_e32 v37, v0
	v_mov_b32_e32 v38, v0
	v_mov_b32_e32 v39, v0
	v_mov_b32_e32 v40, v0
	v_mov_b32_e32 v41, v0
	v_mov_b32_e32 v42, v0
	v_mov_b32_e32 v43, v0
	v_mov_b32_e32 v44, v0
	v_mov_b32_e32 v45, v0
	v_mov_b32_e32 v46, v0
	v_mov_b32_e32 v47, v0
	v_mov_b32_e32 v48, v0
	v_mov_b32_e32 v49, v0
	v_mov_b32_e32 v50, v0
	v_mov_b32_e32 v51, v0
	v_mov_b32_e32 v52, v0
	v_mov_b32_e32 v53, v0
	v_mov_b32_e32 v54, v0
	v_mov_b32_e32 v55, v0
	v_mov_b32_e32 v56, v0
	v_mov_b32_e32 v57, v0
	v_mov_b32_e32 v58, v0
	v_mov_b32_e32 v59, v0
	v_mov_b32_e32 v60, v0
	v_mov_b32_e32 v61, v0
	v_mov_b32_e32 v62, v0
	v_mov_b32_e32 v63, v0
	v_mov_b32_e32 v64, v0
	v_mov_b32_e32 v65, v0
	v_mov_b32_e32 v66, v0
	v_mov_b32_e32 v67, v0
	v_mov_b32_e32 v68, v0
	v_mov_b32_e32 v69, v0
	v_mov_b32_e32 v70, v0
	v_mov_b32_e32 v71, v0
	v_mov_b32_e32 v72, v0
	v_mov_b32_e32 v73, v0
	v_mov_b32_e32 v74, v0
	v_mov_b32_e32 v75, v0
	v_mov_b32_e32 v76, v0
	v_mov_b32_e32 v77, v0
	v_mov_b32_e32 v78, v0
	v_mov_b32_e32 v79, v0
	v_mov_b32_e32 v80, v0
	v_mov_b32_e32 v81, v0
	v_mov_b32_e32 v82, v0
	v_mov_b32_e32 v83, v0
	v_mov_b32_e32 v84, v0
	v_mov_b32_e32 v85, v0
	v_mov_b32_e32 v86, v0
	v_mov_b32_e32 v87, v0
	v_mov_b32_e32 v88, v0
	v_mov_b32_e32 v89, v0
	v_mov_b32_e32 v90, v0
	v_mov_b32_e32 v91, v0
	v_mov_b32_e32 v92, v0
	v_mov_b32_e32 v93, v0
	v_mov_b32_e32 v94, v0
	v_mov_b32_e32 v95, v0
	v_mov_b32_e32 v96, v0
	v_mov_b32_e32 v97, v0
	v_mov_b32_e32 v98, v0
	v_mov_b32_e32 v99, v0
	v_mov_b32_e32 v100, v0
	v_mov_b32_e32 v101, v0
	v_mov_b32_e32 v102, v0
	v_mov_b32_e32 v103, v0
	v_mov_b32_e32 v104, v0
	v_mov_b32_e32 v105, v0
	v_mov_b32_e32 v106, v0
	v_mov_b32_e32 v107, v0
	v_mov_b32_e32 v108, v0
	v_mov_b32_e32 v109, v0
	v_mov_b32_e32 v110, v0
	v_mov_b32_e32 v111, v0
	v_mov_b32_e32 v112, v0
	v_mov_b32_e32 v113, v0
	v_mov_b32_e32 v114, v0
	v_mov_b32_e32 v115, v0
	v_mov_b32_e32 v116, v0
	v_mov_b32_e32 v117, v0
	v_mov_b32_e32 v118, v0
	v_mov_b32_e32 v119, v0
	v_mov_b32_e32 v120, v0
	v_mov_b32_e32 v121, v0
	v_mov_b32_e32 v122, v0
	v_mov_b32_e32 v123, v0
	v_mov_b32_e32 v124, v0
	v_mov_b32_e32 v125, v0
	v_mov_b32_e32 v126, v0
	v_mov_b32_e32 v127, v0
	v_readfirstlane_b32 s56, v166
	v_readfirstlane_b32 s57, v167
	v_readfirstlane_b32 s58, v168
	v_readfirstlane_b32 s59, v169
	v_readfirstlane_b32 s32, v164
	s_nop 3
	s_sub_u32 s56, s56, s32
	s_subb_u32 s57, s57, 0
	s_add_u32 s56, s56, s6
	s_addc_u32 s57, s57, s7
	s_sub_u32 s58, s58, s32
	s_subb_u32 s59, s59, 0
	s_add_u32 s58, s58, s6
	s_addc_u32 s59, s59, s7
	v_add_u32_e32 v240, 0x80, v164
	v_add_u32_e32 v241, 0x20080, v164
	v_add_u32_e32 v242, 0x40080, v164
	v_add_u32_e32 v243, 0x60080, v164
	s_and_b32 s32, s0, 0x10000
	s_add_i32 s32, s32, 16
	v_add3_u32 v132, s32, v181, v182
	v_add3_u32 v165, s32, v183, v182
	v_add_u32_e32 v191, v165, v176
	v_add_u32_e32 v200, v132, v176
	ds_read_b128 v[128:131], v191 offset:32768
	ds_read_b128 v[170:173], v200
	ds_read_b128 v[192:195], v191 offset:36864
	ds_read_b128 v[196:199], v200 offset:4096
	ds_read_b128 v[204:207], v200 offset:8192
	ds_read_b128 v[208:211], v200 offset:12288
.LBB0_743:
	s_add_i32 s8, s0, 0x10000
	s_and_b32 s9, s8, 0x10000
	s_add_i32 s9, s97, s9
	s_mov_b32 m0, s9
	s_nop 0
	global_load_lds_dwordx4 v240, s[56:57]
	s_add_i32 m0, s9, 0x8000
	s_nop 0
	global_load_lds_dwordx4 v240, s[58:59]
	s_add_i32 m0, s9, 0x2000
	s_nop 0
	global_load_lds_dwordx4 v241, s[56:57]
	s_add_i32 m0, s9, 0xa000
	s_nop 0
	global_load_lds_dwordx4 v241, s[58:59]
	s_add_i32 m0, s9, 0x4000
	s_nop 0
	global_load_lds_dwordx4 v242, s[56:57]
	s_add_i32 m0, s9, 0xc000
	s_nop 0
	global_load_lds_dwordx4 v242, s[58:59]
	s_add_i32 m0, s9, 0x6000
	s_nop 0
	global_load_lds_dwordx4 v243, s[56:57]
	s_add_i32 m0, s9, 0xe000
	s_nop 0
	global_load_lds_dwordx4 v243, s[58:59]
	s_add_u32 s56, s56, 0x80
	s_addc_u32 s57, s57, 0
	s_add_u32 s58, s58, 0x80
	s_addc_u32 s59, s59, 0
	v_add_u32_e32 v174, v165, v177
	v_add_u32_e32 v175, v132, v177
	ds_read_b128 v[216:219], v174 offset:32768
	ds_read_b128 v[220:223], v175
	ds_read_b128 v[224:227], v174 offset:36864
	ds_read_b128 v[228:231], v175 offset:4096
	ds_read_b128 v[232:235], v175 offset:8192
	ds_read_b128 v[236:239], v175 offset:12288
	s_waitcnt lgkmcnt(6)
	v_mfma_f32_32x32x16_bf16 v[112:127], v[128:131], v[170:173], v[112:127]
	s_add_u32 s6, s6, 0x80
	s_addc_u32 s7, s7, 0
	s_and_b32 s32, s8, 0x10000
	s_add_i32 s32, s32, 16
	s_cmpk_eq_i32 s6, 0x780
	s_mov_b32 s0, s8
	v_mfma_f32_32x32x16_bf16 v[96:111], v[128:131], v[196:199], v[96:111]
	v_mfma_f32_32x32x16_bf16 v[80:95], v[128:131], v[204:207], v[80:95]
	v_mfma_f32_32x32x16_bf16 v[64:79], v[128:131], v[208:211], v[64:79]
	v_mfma_f32_32x32x16_bf16 v[48:63], v[192:195], v[170:173], v[48:63]
	v_mfma_f32_32x32x16_bf16 v[32:47], v[192:195], v[196:199], v[32:47]
	v_mfma_f32_32x32x16_bf16 v[16:31], v[192:195], v[204:207], v[16:31]
	v_mfma_f32_32x32x16_bf16 v[0:15], v[192:195], v[208:211], v[0:15]
	v_add_u32_e32 v174, v165, v178
	v_add_u32_e32 v175, v132, v178
	ds_read_b128 v[128:131], v174 offset:32768
	ds_read_b128 v[170:173], v175
	ds_read_b128 v[192:195], v174 offset:36864
	ds_read_b128 v[196:199], v175 offset:4096
	ds_read_b128 v[204:207], v175 offset:8192
	ds_read_b128 v[208:211], v175 offset:12288
	s_waitcnt lgkmcnt(6)
; #define MFMA(a, b, c) __builtin_amdgcn_mfma_f32_32x32x16_bf16((a), (b), (c), 0, 0, 0)
; #define G_BARRIER() { asm volatile("s_waitcnt vmcnt(0) lgkmcnt(0)" ::: "memory"); __builtin_amdgcn_s_barrier(); asm volatile("" ::: "memory"); }
;     ...
;         for (int kt = 0; kt < nk; ++kt) {
;             if (kt + 1 < nk) { G_DMA(kt + 1, (kt + 1) & 1); }
;             const unsigned char* sa = lds + (kt & 1) * 65536 + (wt * 32 * TB + r) * 128;
;             const unsigned char* sw = lds + (kt & 1) * 65536 + 32768 + (wf * 64 + r) * 128;
; #pragma unroll
;             for (int ks = 0; ks < 4; ++ks) {
;                 bf16x8 wfr[2], afr[TB];
; #pragma unroll
;                 for (int fb = 0; fb < 2; ++fb) wfr[fb] = *(const bf16x8*)(sw + fb * 4096 + koff[ks]);
; #pragma unroll
;                 for (int tb = 0; tb < TB; ++tb) afr[tb] = *(const bf16x8*)(sa + tb * 4096 + koff[ks]);
; #pragma unroll
;                 for (int fb = 0; fb < 2; ++fb)
; #pragma unroll
;                     for (int tb = 0; tb < TB; ++tb) acc[fb][tb] = MFMA(wfr[fb], afr[tb], acc[fb][tb]);
;             }
;             G_BARRIER();
;         }
	v_mfma_f32_32x32x16_bf16 v[112:127], v[216:219], v[220:223], v[112:127]
	v_mfma_f32_32x32x16_bf16 v[96:111], v[216:219], v[228:231], v[96:111]
	v_mfma_f32_32x32x16_bf16 v[80:95], v[216:219], v[232:235], v[80:95]
	v_mfma_f32_32x32x16_bf16 v[64:79], v[216:219], v[236:239], v[64:79]
	v_mfma_f32_32x32x16_bf16 v[48:63], v[224:227], v[220:223], v[48:63]
	v_mfma_f32_32x32x16_bf16 v[32:47], v[224:227], v[228:231], v[32:47]
	v_mfma_f32_32x32x16_bf16 v[16:31], v[224:227], v[232:235], v[16:31]
	v_mfma_f32_32x32x16_bf16 v[0:15], v[224:227], v[236:239], v[0:15]
	v_add_u32_e32 v165, v165, v179
	v_add_u32_e32 v132, v132, v179
	ds_read_b128 v[216:219], v165 offset:32768
	ds_read_b128 v[220:223], v132
	ds_read_b128 v[224:227], v165 offset:36864
	ds_read_b128 v[228:231], v132 offset:4096
	ds_read_b128 v[232:235], v132 offset:8192
	ds_read_b128 v[236:239], v132 offset:12288
	s_waitcnt lgkmcnt(6)
	v_mfma_f32_32x32x16_bf16 v[112:127], v[128:131], v[170:173], v[112:127]
	v_mfma_f32_32x32x16_bf16 v[96:111], v[128:131], v[196:199], v[96:111]
	v_mfma_f32_32x32x16_bf16 v[80:95], v[128:131], v[204:207], v[80:95]
	v_mfma_f32_32x32x16_bf16 v[64:79], v[128:131], v[208:211], v[64:79]
	v_mfma_f32_32x32x16_bf16 v[48:63], v[192:195], v[170:173], v[48:63]
	v_mfma_f32_32x32x16_bf16 v[32:47], v[192:195], v[196:199], v[32:47]
	v_mfma_f32_32x32x16_bf16 v[16:31], v[192:195], v[204:207], v[16:31]
	v_mfma_f32_32x32x16_bf16 v[0:15], v[192:195], v[208:211], v[0:15]
	s_waitcnt vmcnt(0) lgkmcnt(0)
	s_barrier
	v_add3_u32 v132, s32, v181, v182
	v_add3_u32 v165, s32, v183, v182
	v_add_u32_e32 v191, v165, v176
	v_add_u32_e32 v200, v132, v176
	ds_read_b128 v[128:131], v191 offset:32768
	ds_read_b128 v[170:173], v200
	ds_read_b128 v[192:195], v191 offset:36864
	ds_read_b128 v[196:199], v200 offset:4096
	ds_read_b128 v[204:207], v200 offset:8192
	ds_read_b128 v[208:211], v200 offset:12288
	v_mfma_f32_32x32x16_bf16 v[112:127], v[216:219], v[220:223], v[112:127]
	v_mfma_f32_32x32x16_bf16 v[96:111], v[216:219], v[228:231], v[96:111]
	v_mfma_f32_32x32x16_bf16 v[80:95], v[216:219], v[232:235], v[80:95]
	v_mfma_f32_32x32x16_bf16 v[64:79], v[216:219], v[236:239], v[64:79]
	v_mfma_f32_32x32x16_bf16 v[48:63], v[224:227], v[220:223], v[48:63]
	v_mfma_f32_32x32x16_bf16 v[32:47], v[224:227], v[228:231], v[32:47]
	v_mfma_f32_32x32x16_bf16 v[16:31], v[224:227], v[232:235], v[16:31]
	v_mfma_f32_32x32x16_bf16 v[0:15], v[224:227], v[236:239], v[0:15]
	s_cbranch_scc0 .LBB0_743
; #define GAS __attribute__((address_space(1)))
; #define MFMA(a, b, c) __builtin_amdgcn_mfma_f32_32x32x16_bf16((a), (b), (c), 0, 0, 0)
; #define G_BARRIER() { asm volatile("s_waitcnt vmcnt(0) lgkmcnt(0)" ::: "memory"); __builtin_amdgcn_s_barrier(); asm volatile("" ::: "memory"); }
;     ...
;         for (int kt = 0; kt < nk; ++kt) {
;             if (kt + 1 < nk) { G_DMA(kt + 1, (kt + 1) & 1); }
;             const unsigned char* sa = lds + (kt & 1) * 65536 + (wt * 32 * TB + r) * 128;
;             const unsigned char* sw = lds + (kt & 1) * 65536 + 32768 + (wf * 64 + r) * 128;
; #pragma unroll
;             for (int ks = 0; ks < 4; ++ks) {
;                 bf16x8 wfr[2], afr[TB];
; #pragma unroll
;                 for (int fb = 0; fb < 2; ++fb) wfr[fb] = *(const bf16x8*)(sw + fb * 4096 + koff[ks]);
; #pragma unroll
;                 for (int tb = 0; tb < TB; ++tb) afr[tb] = *(const bf16x8*)(sa + tb * 4096 + koff[ks]);
; #pragma unroll
;                 for (int fb = 0; fb < 2; ++fb)
; #pragma unroll
;                     for (int tb = 0; tb < TB; ++tb) acc[fb][tb] = MFMA(wfr[fb], afr[tb], acc[fb][tb]);
;             }
;             G_BARRIER();
;         }
;         const int un = u + nslots;
;         if (un < nloc) {
;             Ag = (const GAS bf16_t*)(A + (size_t)(xcd + nx * (un / Ntiles)) * RM * K) + dsrc; Wg = (const GAS bf16_t*)(Wt + (size_t)(un % Ntiles) * 256 * K) + dsrc;
;             G_DMA(0, 0);
;         }
	v_add_u32_e32 v132, v187, v176
	ds_read_b128 v[128:131], v132
	v_add_u32_e32 v165, v186, v176
	ds_read_b128 v[170:173], v165
	ds_read_b128 v[192:195], v165 offset:4096
	ds_read_b128 v[196:199], v165 offset:8192
	ds_read_b128 v[204:207], v165 offset:12288
	v_add_u32_e32 v165, v186, v177
	s_add_i32 s0, s1, s71
	s_cmp_ge_i32 s0, s72
	s_waitcnt lgkmcnt(0)
	v_mfma_f32_32x32x16_bf16 v[112:127], v[128:131], v[170:173], v[112:127]
	s_cselect_b64 s[60:61], -1, 0
	s_cmp_lt_i32 s0, s72
	v_mfma_f32_32x32x16_bf16 v[96:111], v[128:131], v[192:195], v[96:111]
	v_mfma_f32_32x32x16_bf16 v[80:95], v[128:131], v[196:199], v[80:95]
	v_mfma_f32_32x32x16_bf16 v[64:79], v[128:131], v[204:207], v[64:79]
	ds_read_b128 v[128:131], v132 offset:4096
	v_add_u32_e32 v132, v187, v177
	s_waitcnt lgkmcnt(0)
	v_mfma_f32_32x32x16_bf16 v[48:63], v[128:131], v[170:173], v[48:63]
	ds_read_b128 v[170:173], v165
	v_mfma_f32_32x32x16_bf16 v[32:47], v[128:131], v[192:195], v[32:47]
	ds_read_b128 v[192:195], v165 offset:4096
	v_mfma_f32_32x32x16_bf16 v[16:31], v[128:131], v[196:199], v[16:31]
	ds_read_b128 v[196:199], v165 offset:8192
	v_mfma_f32_32x32x16_bf16 v[0:15], v[128:131], v[204:207], v[0:15]
	ds_read_b128 v[128:131], v132
	ds_read_b128 v[204:207], v165 offset:12288
	v_add_u32_e32 v165, v186, v178
	s_waitcnt lgkmcnt(0)
	v_mfma_f32_32x32x16_bf16 v[112:127], v[128:131], v[170:173], v[112:127]
	v_mfma_f32_32x32x16_bf16 v[96:111], v[128:131], v[192:195], v[96:111]
	v_mfma_f32_32x32x16_bf16 v[80:95], v[128:131], v[196:199], v[80:95]
	v_mfma_f32_32x32x16_bf16 v[64:79], v[128:131], v[204:207], v[64:79]
	ds_read_b128 v[128:131], v132 offset:4096
	v_add_u32_e32 v132, v187, v178
	s_waitcnt lgkmcnt(0)
	v_mfma_f32_32x32x16_bf16 v[48:63], v[128:131], v[170:173], v[48:63]
	ds_read_b128 v[170:173], v165
	v_mfma_f32_32x32x16_bf16 v[32:47], v[128:131], v[192:195], v[32:47]
	ds_read_b128 v[192:195], v165 offset:4096
	v_mfma_f32_32x32x16_bf16 v[16:31], v[128:131], v[196:199], v[16:31]
	ds_read_b128 v[196:199], v165 offset:8192
	v_mfma_f32_32x32x16_bf16 v[0:15], v[128:131], v[204:207], v[0:15]
	ds_read_b128 v[128:131], v132
	ds_read_b128 v[204:207], v165 offset:12288
	v_add_u32_e32 v165, v186, v179
	s_waitcnt lgkmcnt(0)
	v_mfma_f32_32x32x16_bf16 v[112:127], v[128:131], v[170:173], v[112:127]
	v_mfma_f32_32x32x16_bf16 v[96:111], v[128:131], v[192:195], v[96:111]
	v_mfma_f32_32x32x16_bf16 v[80:95], v[128:131], v[196:199], v[80:95]
	v_mfma_f32_32x32x16_bf16 v[64:79], v[128:131], v[204:207], v[64:79]
	ds_read_b128 v[128:131], v132 offset:4096
	v_add_u32_e32 v132, v187, v179
	s_waitcnt lgkmcnt(0)
	v_mfma_f32_32x32x16_bf16 v[48:63], v[128:131], v[170:173], v[48:63]
	ds_read_b128 v[170:173], v165
	v_mfma_f32_32x32x16_bf16 v[32:47], v[128:131], v[192:195], v[32:47]
	ds_read_b128 v[192:195], v165 offset:4096
	v_mfma_f32_32x32x16_bf16 v[16:31], v[128:131], v[196:199], v[16:31]
	ds_read_b128 v[196:199], v165 offset:8192
	v_mfma_f32_32x32x16_bf16 v[0:15], v[128:131], v[204:207], v[0:15]
	ds_read_b128 v[128:131], v132
	ds_read_b128 v[204:207], v165 offset:12288
	s_waitcnt lgkmcnt(0)
	v_mfma_f32_32x32x16_bf16 v[112:127], v[128:131], v[170:173], v[112:127]
	v_mfma_f32_32x32x16_bf16 v[96:111], v[128:131], v[192:195], v[96:111]
	v_mfma_f32_32x32x16_bf16 v[80:95], v[128:131], v[196:199], v[80:95]
	v_mfma_f32_32x32x16_bf16 v[64:79], v[128:131], v[204:207], v[64:79]
	ds_read_b128 v[128:131], v132 offset:4096
	s_waitcnt vmcnt(0) lgkmcnt(0)
	s_barrier
	s_waitcnt lgkmcnt(0)
	v_mfma_f32_32x32x16_bf16 v[48:63], v[128:131], v[170:173], v[48:63]
	v_mfma_f32_32x32x16_bf16 v[32:47], v[128:131], v[192:195], v[32:47]
	v_mfma_f32_32x32x16_bf16 v[16:31], v[128:131], v[196:199], v[16:31]
	v_mfma_f32_32x32x16_bf16 v[0:15], v[128:131], v[204:207], v[0:15]
	s_cbranch_scc0 .LBB0_746
	s_mul_hi_i32 s6, s0, 0x2aaaaaab
	s_lshr_b32 s7, s6, 31
	s_add_i32 s8, s6, s7
	s_lshl_b32 s6, s8, s67
	s_add_i32 s6, s6, s70
	s_ashr_i32 s7, s6, 31
	s_lshl_b64 s[6:7], s[6:7], 19
	s_add_u32 s6, s38, s6
	s_mul_i32 s8, s8, 6
	s_addc_u32 s7, s39, s7
	s_sub_i32 s8, s0, s8
	s_ashr_i32 s9, s8, 31
	s_lshl_b64 s[8:9], s[8:9], 19
	s_mov_b32 m0, s97
	v_mov_b32_e32 v165, v133
	s_add_u32 s8, s40, s8
	v_lshl_add_u64 v[166:167], s[6:7], 0, v[164:165]
	s_addc_u32 s9, s41, s9
	global_load_lds_dwordx4 v164, s[6:7]
	s_add_i32 m0, s97, 0x8000
	v_lshl_add_u64 v[168:169], s[8:9], 0, v[164:165]
	global_load_lds_dwordx4 v164, s[8:9]
	v_lshl_add_u64 v[128:129], v[166:167], 0, s[44:45]
	s_add_i32 m0, s97, 0x2000
	s_nop 0
	global_load_lds_dwordx4 v[128:129], off
	v_lshl_add_u64 v[128:129], v[168:169], 0, s[44:45]
	s_add_i32 m0, s97, 0xa000
	s_nop 0
	global_load_lds_dwordx4 v[128:129], off
	v_lshl_add_u64 v[128:129], v[166:167], 0, s[46:47]
	s_add_i32 m0, s97, 0x4000
	s_nop 0
	global_load_lds_dwordx4 v[128:129], off
	v_lshl_add_u64 v[128:129], v[168:169], 0, s[46:47]
	s_add_i32 m0, s97, 0xc000
	s_nop 0
	global_load_lds_dwordx4 v[128:129], off
	v_lshl_add_u64 v[128:129], v[166:167], 0, s[48:49]
	s_add_i32 m0, s97, 0x6000
	s_nop 0
	global_load_lds_dwordx4 v[128:129], off
	v_lshl_add_u64 v[128:129], v[168:169], 0, s[48:49]
	s_add_i32 m0, s97, 0xe000
	s_nop 0
	global_load_lds_dwordx4 v[128:129], off
